# EVIN-tail shift GEMVs (layers 0 and 2): rolling reload pipeline keeps 8 weight-row loads in flight instead of load-8-then-drain
# baseline (speedup 1.0000x reference)
.LBB0_370:
	v_mov_b32_e32 v140, v24
	v_mov_b32_e32 v141, v25
	v_lshl_add_u64 v[142:143], v[140:141], 0, s[26:27]
	v_lshl_add_u64 v[144:145], v[142:143], 0, s[26:27]
	v_lshl_add_u64 v[146:147], v[144:145], 0, s[26:27]
	v_lshl_add_u64 v[148:149], v[146:147], 0, s[26:27]
	v_lshl_add_u64 v[150:151], v[148:149], 0, s[26:27]
	v_lshl_add_u64 v[152:153], v[150:151], 0, s[26:27]
	v_lshl_add_u64 v[154:155], v[152:153], 0, s[26:27]
	global_load_dwordx4 v[16:19], v[140:141], off
	global_load_dwordx4 v[38:41], v[142:143], off
	global_load_dwordx4 v[42:45], v[144:145], off
	global_load_dwordx4 v[46:49], v[146:147], off
	global_load_dwordx4 v[50:53], v[148:149], off
	global_load_dwordx4 v[54:57], v[150:151], off
	global_load_dwordx4 v[58:61], v[152:153], off
	global_load_dwordx4 v[62:65], v[154:155], off
.Lgemv2a_loop:
	v_add_u32_e32 v37, s48, v32
	s_waitcnt vmcnt(8)
	ds_bpermute_b32 v66, v37, v33
	ds_bpermute_b32 v68, v37, v34
	ds_bpermute_b32 v70, v37, v35
	ds_bpermute_b32 v72, v37, v36
	ds_bpermute_b32 v74, v37, v33 offset:4
	ds_bpermute_b32 v76, v37, v34 offset:4
	ds_bpermute_b32 v78, v37, v35 offset:4
	ds_bpermute_b32 v80, v37, v36 offset:4
	ds_bpermute_b32 v82, v37, v33 offset:8
	ds_bpermute_b32 v84, v37, v34 offset:8
	ds_bpermute_b32 v86, v37, v35 offset:8
	ds_bpermute_b32 v88, v37, v36 offset:8
	ds_bpermute_b32 v90, v37, v33 offset:12
	ds_bpermute_b32 v92, v37, v34 offset:12
	ds_bpermute_b32 v94, v37, v35 offset:12
	ds_bpermute_b32 v96, v37, v36 offset:12
	ds_bpermute_b32 v98, v37, v33 offset:16
	ds_bpermute_b32 v100, v37, v34 offset:16
	ds_bpermute_b32 v26, v37, v35 offset:16
	ds_bpermute_b32 v102, v37, v36 offset:16
	ds_bpermute_b32 v104, v37, v33 offset:20
	ds_bpermute_b32 v106, v37, v34 offset:20
	ds_bpermute_b32 v108, v37, v35 offset:20
	ds_bpermute_b32 v110, v37, v36 offset:20
	ds_bpermute_b32 v112, v37, v33 offset:24
	ds_bpermute_b32 v114, v37, v34 offset:24
	ds_bpermute_b32 v116, v37, v35 offset:24
	ds_bpermute_b32 v118, v37, v36 offset:24
	ds_bpermute_b32 v120, v37, v33 offset:28
	ds_bpermute_b32 v122, v37, v34 offset:28
	ds_bpermute_b32 v124, v37, v35 offset:28
	ds_bpermute_b32 v126, v37, v36 offset:28
	s_add_i32 s48, s48, 32
	s_cmpk_eq_i32 s48, 0xe0
	s_waitcnt vmcnt(7)
	s_waitcnt lgkmcnt(14)
	v_pk_fma_f32 v[2:3], v[18:19], v[66:67], v[2:3] op_sel_hi:[1,0,1]
	v_pk_fma_f32 v[0:1], v[16:17], v[66:67], v[0:1] op_sel_hi:[1,0,1]
	v_pk_fma_f32 v[6:7], v[18:19], v[68:69], v[6:7] op_sel_hi:[1,0,1]
	v_pk_fma_f32 v[4:5], v[16:17], v[68:69], v[4:5] op_sel_hi:[1,0,1]
	v_pk_fma_f32 v[10:11], v[18:19], v[70:71], v[10:11] op_sel_hi:[1,0,1]
	v_pk_fma_f32 v[8:9], v[16:17], v[70:71], v[8:9] op_sel_hi:[1,0,1]
	v_pk_fma_f32 v[14:15], v[18:19], v[72:73], v[14:15] op_sel_hi:[1,0,1]
	v_pk_fma_f32 v[12:13], v[16:17], v[72:73], v[12:13] op_sel_hi:[1,0,1]
	v_lshl_add_u64 v[140:141], v[140:141], 0, s[20:21]
	global_load_dwordx4 v[16:19], v[140:141], off
	s_waitcnt vmcnt(7)
	v_pk_fma_f32 v[2:3], v[40:41], v[74:75], v[2:3] op_sel_hi:[1,0,1]
	v_pk_fma_f32 v[0:1], v[38:39], v[74:75], v[0:1] op_sel_hi:[1,0,1]
	v_pk_fma_f32 v[6:7], v[40:41], v[76:77], v[6:7] op_sel_hi:[1,0,1]
	v_pk_fma_f32 v[4:5], v[38:39], v[76:77], v[4:5] op_sel_hi:[1,0,1]
	v_pk_fma_f32 v[10:11], v[40:41], v[78:79], v[10:11] op_sel_hi:[1,0,1]
	v_pk_fma_f32 v[8:9], v[38:39], v[78:79], v[8:9] op_sel_hi:[1,0,1]
	v_pk_fma_f32 v[14:15], v[40:41], v[80:81], v[14:15] op_sel_hi:[1,0,1]
	v_pk_fma_f32 v[12:13], v[38:39], v[80:81], v[12:13] op_sel_hi:[1,0,1]
	v_lshl_add_u64 v[142:143], v[142:143], 0, s[20:21]
	global_load_dwordx4 v[38:41], v[142:143], off
	s_waitcnt vmcnt(7)
	v_pk_fma_f32 v[2:3], v[44:45], v[82:83], v[2:3] op_sel_hi:[1,0,1]
	v_pk_fma_f32 v[0:1], v[42:43], v[82:83], v[0:1] op_sel_hi:[1,0,1]
	v_pk_fma_f32 v[6:7], v[44:45], v[84:85], v[6:7] op_sel_hi:[1,0,1]
	v_pk_fma_f32 v[4:5], v[42:43], v[84:85], v[4:5] op_sel_hi:[1,0,1]
	v_pk_fma_f32 v[10:11], v[44:45], v[86:87], v[10:11] op_sel_hi:[1,0,1]
	v_pk_fma_f32 v[8:9], v[42:43], v[86:87], v[8:9] op_sel_hi:[1,0,1]
	v_pk_fma_f32 v[14:15], v[44:45], v[88:89], v[14:15] op_sel_hi:[1,0,1]
	v_pk_fma_f32 v[12:13], v[42:43], v[88:89], v[12:13] op_sel_hi:[1,0,1]
	v_lshl_add_u64 v[144:145], v[144:145], 0, s[20:21]
	global_load_dwordx4 v[42:45], v[144:145], off
	s_waitcnt vmcnt(7)
	v_pk_fma_f32 v[2:3], v[48:49], v[90:91], v[2:3] op_sel_hi:[1,0,1]
	v_pk_fma_f32 v[0:1], v[46:47], v[90:91], v[0:1] op_sel_hi:[1,0,1]
	v_pk_fma_f32 v[6:7], v[48:49], v[92:93], v[6:7] op_sel_hi:[1,0,1]
	v_pk_fma_f32 v[4:5], v[46:47], v[92:93], v[4:5] op_sel_hi:[1,0,1]
	v_pk_fma_f32 v[10:11], v[48:49], v[94:95], v[10:11] op_sel_hi:[1,0,1]
	v_pk_fma_f32 v[8:9], v[46:47], v[94:95], v[8:9] op_sel_hi:[1,0,1]
	v_pk_fma_f32 v[14:15], v[48:49], v[96:97], v[14:15] op_sel_hi:[1,0,1]
	v_pk_fma_f32 v[12:13], v[46:47], v[96:97], v[12:13] op_sel_hi:[1,0,1]
	v_lshl_add_u64 v[146:147], v[146:147], 0, s[20:21]
	global_load_dwordx4 v[46:49], v[146:147], off
	s_waitcnt vmcnt(7)
	v_pk_fma_f32 v[2:3], v[52:53], v[98:99], v[2:3] op_sel_hi:[1,0,1]
	v_pk_fma_f32 v[0:1], v[50:51], v[98:99], v[0:1] op_sel_hi:[1,0,1]
	v_pk_fma_f32 v[6:7], v[52:53], v[100:101], v[6:7] op_sel_hi:[1,0,1]
	v_pk_fma_f32 v[4:5], v[50:51], v[100:101], v[4:5] op_sel_hi:[1,0,1]
	s_waitcnt lgkmcnt(13)
	v_pk_fma_f32 v[10:11], v[52:53], v[26:27], v[10:11] op_sel_hi:[1,0,1]
	v_pk_fma_f32 v[8:9], v[50:51], v[26:27], v[8:9] op_sel_hi:[1,0,1]
	s_waitcnt lgkmcnt(12)
	v_pk_fma_f32 v[14:15], v[52:53], v[102:103], v[14:15] op_sel_hi:[1,0,1]
	v_pk_fma_f32 v[12:13], v[50:51], v[102:103], v[12:13] op_sel_hi:[1,0,1]
	v_lshl_add_u64 v[148:149], v[148:149], 0, s[20:21]
	global_load_dwordx4 v[50:53], v[148:149], off
	s_waitcnt vmcnt(7)
	s_waitcnt lgkmcnt(11)
	v_pk_fma_f32 v[2:3], v[56:57], v[104:105], v[2:3] op_sel_hi:[1,0,1]
	v_pk_fma_f32 v[0:1], v[54:55], v[104:105], v[0:1] op_sel_hi:[1,0,1]
	s_waitcnt lgkmcnt(10)
	v_pk_fma_f32 v[6:7], v[56:57], v[106:107], v[6:7] op_sel_hi:[1,0,1]
	v_pk_fma_f32 v[4:5], v[54:55], v[106:107], v[4:5] op_sel_hi:[1,0,1]
	s_waitcnt lgkmcnt(9)
	v_pk_fma_f32 v[10:11], v[56:57], v[108:109], v[10:11] op_sel_hi:[1,0,1]
	v_pk_fma_f32 v[8:9], v[54:55], v[108:109], v[8:9] op_sel_hi:[1,0,1]
	s_waitcnt lgkmcnt(8)
	v_pk_fma_f32 v[14:15], v[56:57], v[110:111], v[14:15] op_sel_hi:[1,0,1]
	v_pk_fma_f32 v[12:13], v[54:55], v[110:111], v[12:13] op_sel_hi:[1,0,1]
	v_lshl_add_u64 v[150:151], v[150:151], 0, s[20:21]
	global_load_dwordx4 v[54:57], v[150:151], off
	s_waitcnt vmcnt(7)
	s_waitcnt lgkmcnt(7)
	v_pk_fma_f32 v[2:3], v[60:61], v[112:113], v[2:3] op_sel_hi:[1,0,1]
	v_pk_fma_f32 v[0:1], v[58:59], v[112:113], v[0:1] op_sel_hi:[1,0,1]
	s_waitcnt lgkmcnt(6)
	v_pk_fma_f32 v[6:7], v[60:61], v[114:115], v[6:7] op_sel_hi:[1,0,1]
	v_pk_fma_f32 v[4:5], v[58:59], v[114:115], v[4:5] op_sel_hi:[1,0,1]
	s_waitcnt lgkmcnt(5)
	v_pk_fma_f32 v[10:11], v[60:61], v[116:117], v[10:11] op_sel_hi:[1,0,1]
	v_pk_fma_f32 v[8:9], v[58:59], v[116:117], v[8:9] op_sel_hi:[1,0,1]
	s_waitcnt lgkmcnt(4)
	v_pk_fma_f32 v[14:15], v[60:61], v[118:119], v[14:15] op_sel_hi:[1,0,1]
	v_pk_fma_f32 v[12:13], v[58:59], v[118:119], v[12:13] op_sel_hi:[1,0,1]
	v_lshl_add_u64 v[152:153], v[152:153], 0, s[20:21]
	global_load_dwordx4 v[58:61], v[152:153], off
	s_waitcnt vmcnt(7)
	s_waitcnt lgkmcnt(3)
	v_pk_fma_f32 v[2:3], v[64:65], v[120:121], v[2:3] op_sel_hi:[1,0,1]
	v_pk_fma_f32 v[0:1], v[62:63], v[120:121], v[0:1] op_sel_hi:[1,0,1]
	s_waitcnt lgkmcnt(2)
	v_pk_fma_f32 v[6:7], v[64:65], v[122:123], v[6:7] op_sel_hi:[1,0,1]
	v_pk_fma_f32 v[4:5], v[62:63], v[122:123], v[4:5] op_sel_hi:[1,0,1]
	s_waitcnt lgkmcnt(1)
	v_pk_fma_f32 v[10:11], v[64:65], v[124:125], v[10:11] op_sel_hi:[1,0,1]
	v_pk_fma_f32 v[8:9], v[62:63], v[124:125], v[8:9] op_sel_hi:[1,0,1]
	s_waitcnt lgkmcnt(0)
	v_pk_fma_f32 v[14:15], v[64:65], v[126:127], v[14:15] op_sel_hi:[1,0,1]
	v_pk_fma_f32 v[12:13], v[62:63], v[126:127], v[12:13] op_sel_hi:[1,0,1]
	v_lshl_add_u64 v[154:155], v[154:155], 0, s[20:21]
	global_load_dwordx4 v[62:65], v[154:155], off
	s_cbranch_scc0 .Lgemv2a_loop
	v_add_u32_e32 v37, s48, v32
	s_waitcnt vmcnt(8)
	ds_bpermute_b32 v66, v37, v33
	ds_bpermute_b32 v68, v37, v34
	ds_bpermute_b32 v70, v37, v35
	ds_bpermute_b32 v72, v37, v36
	ds_bpermute_b32 v74, v37, v33 offset:4
	ds_bpermute_b32 v76, v37, v34 offset:4
	ds_bpermute_b32 v78, v37, v35 offset:4
	ds_bpermute_b32 v80, v37, v36 offset:4
	ds_bpermute_b32 v82, v37, v33 offset:8
	ds_bpermute_b32 v84, v37, v34 offset:8
	ds_bpermute_b32 v86, v37, v35 offset:8
	ds_bpermute_b32 v88, v37, v36 offset:8
	ds_bpermute_b32 v90, v37, v33 offset:12
	ds_bpermute_b32 v92, v37, v34 offset:12
	ds_bpermute_b32 v94, v37, v35 offset:12
	ds_bpermute_b32 v96, v37, v36 offset:12
	ds_bpermute_b32 v98, v37, v33 offset:16
	ds_bpermute_b32 v100, v37, v34 offset:16
	ds_bpermute_b32 v26, v37, v35 offset:16
	ds_bpermute_b32 v102, v37, v36 offset:16
	ds_bpermute_b32 v104, v37, v33 offset:20
	ds_bpermute_b32 v106, v37, v34 offset:20
	ds_bpermute_b32 v108, v37, v35 offset:20
	ds_bpermute_b32 v110, v37, v36 offset:20
	ds_bpermute_b32 v112, v37, v33 offset:24
	ds_bpermute_b32 v114, v37, v34 offset:24
	ds_bpermute_b32 v116, v37, v35 offset:24
	ds_bpermute_b32 v118, v37, v36 offset:24
	ds_bpermute_b32 v120, v37, v33 offset:28
	ds_bpermute_b32 v122, v37, v34 offset:28
	ds_bpermute_b32 v124, v37, v35 offset:28
	ds_bpermute_b32 v126, v37, v36 offset:28
	s_add_i32 s48, s48, 32
	s_waitcnt vmcnt(7)
	s_waitcnt lgkmcnt(14)
	v_pk_fma_f32 v[2:3], v[18:19], v[66:67], v[2:3] op_sel_hi:[1,0,1]
	v_pk_fma_f32 v[0:1], v[16:17], v[66:67], v[0:1] op_sel_hi:[1,0,1]
	v_pk_fma_f32 v[6:7], v[18:19], v[68:69], v[6:7] op_sel_hi:[1,0,1]
	v_pk_fma_f32 v[4:5], v[16:17], v[68:69], v[4:5] op_sel_hi:[1,0,1]
	v_pk_fma_f32 v[10:11], v[18:19], v[70:71], v[10:11] op_sel_hi:[1,0,1]
	v_pk_fma_f32 v[8:9], v[16:17], v[70:71], v[8:9] op_sel_hi:[1,0,1]
	v_pk_fma_f32 v[14:15], v[18:19], v[72:73], v[14:15] op_sel_hi:[1,0,1]
	v_pk_fma_f32 v[12:13], v[16:17], v[72:73], v[12:13] op_sel_hi:[1,0,1]
	s_waitcnt vmcnt(6)
	v_pk_fma_f32 v[2:3], v[40:41], v[74:75], v[2:3] op_sel_hi:[1,0,1]
	v_pk_fma_f32 v[0:1], v[38:39], v[74:75], v[0:1] op_sel_hi:[1,0,1]
	v_pk_fma_f32 v[6:7], v[40:41], v[76:77], v[6:7] op_sel_hi:[1,0,1]
	v_pk_fma_f32 v[4:5], v[38:39], v[76:77], v[4:5] op_sel_hi:[1,0,1]
	v_pk_fma_f32 v[10:11], v[40:41], v[78:79], v[10:11] op_sel_hi:[1,0,1]
	v_pk_fma_f32 v[8:9], v[38:39], v[78:79], v[8:9] op_sel_hi:[1,0,1]
	v_pk_fma_f32 v[14:15], v[40:41], v[80:81], v[14:15] op_sel_hi:[1,0,1]
	v_pk_fma_f32 v[12:13], v[38:39], v[80:81], v[12:13] op_sel_hi:[1,0,1]
	s_waitcnt vmcnt(5)
	v_pk_fma_f32 v[2:3], v[44:45], v[82:83], v[2:3] op_sel_hi:[1,0,1]
	v_pk_fma_f32 v[0:1], v[42:43], v[82:83], v[0:1] op_sel_hi:[1,0,1]
	v_pk_fma_f32 v[6:7], v[44:45], v[84:85], v[6:7] op_sel_hi:[1,0,1]
	v_pk_fma_f32 v[4:5], v[42:43], v[84:85], v[4:5] op_sel_hi:[1,0,1]
	v_pk_fma_f32 v[10:11], v[44:45], v[86:87], v[10:11] op_sel_hi:[1,0,1]
	v_pk_fma_f32 v[8:9], v[42:43], v[86:87], v[8:9] op_sel_hi:[1,0,1]
	v_pk_fma_f32 v[14:15], v[44:45], v[88:89], v[14:15] op_sel_hi:[1,0,1]
	v_pk_fma_f32 v[12:13], v[42:43], v[88:89], v[12:13] op_sel_hi:[1,0,1]
	s_waitcnt vmcnt(4)
	v_pk_fma_f32 v[2:3], v[48:49], v[90:91], v[2:3] op_sel_hi:[1,0,1]
	v_pk_fma_f32 v[0:1], v[46:47], v[90:91], v[0:1] op_sel_hi:[1,0,1]
	v_pk_fma_f32 v[6:7], v[48:49], v[92:93], v[6:7] op_sel_hi:[1,0,1]
	v_pk_fma_f32 v[4:5], v[46:47], v[92:93], v[4:5] op_sel_hi:[1,0,1]
	v_pk_fma_f32 v[10:11], v[48:49], v[94:95], v[10:11] op_sel_hi:[1,0,1]
	v_pk_fma_f32 v[8:9], v[46:47], v[94:95], v[8:9] op_sel_hi:[1,0,1]
	v_pk_fma_f32 v[14:15], v[48:49], v[96:97], v[14:15] op_sel_hi:[1,0,1]
	v_pk_fma_f32 v[12:13], v[46:47], v[96:97], v[12:13] op_sel_hi:[1,0,1]
	s_waitcnt vmcnt(3)
	v_pk_fma_f32 v[2:3], v[52:53], v[98:99], v[2:3] op_sel_hi:[1,0,1]
	v_pk_fma_f32 v[0:1], v[50:51], v[98:99], v[0:1] op_sel_hi:[1,0,1]
	v_pk_fma_f32 v[6:7], v[52:53], v[100:101], v[6:7] op_sel_hi:[1,0,1]
	v_pk_fma_f32 v[4:5], v[50:51], v[100:101], v[4:5] op_sel_hi:[1,0,1]
	s_waitcnt lgkmcnt(13)
	v_pk_fma_f32 v[10:11], v[52:53], v[26:27], v[10:11] op_sel_hi:[1,0,1]
	v_pk_fma_f32 v[8:9], v[50:51], v[26:27], v[8:9] op_sel_hi:[1,0,1]
	s_waitcnt lgkmcnt(12)
	v_pk_fma_f32 v[14:15], v[52:53], v[102:103], v[14:15] op_sel_hi:[1,0,1]
	v_pk_fma_f32 v[12:13], v[50:51], v[102:103], v[12:13] op_sel_hi:[1,0,1]
	s_waitcnt vmcnt(2)
	s_waitcnt lgkmcnt(11)
	v_pk_fma_f32 v[2:3], v[56:57], v[104:105], v[2:3] op_sel_hi:[1,0,1]
	v_pk_fma_f32 v[0:1], v[54:55], v[104:105], v[0:1] op_sel_hi:[1,0,1]
	s_waitcnt lgkmcnt(10)
	v_pk_fma_f32 v[6:7], v[56:57], v[106:107], v[6:7] op_sel_hi:[1,0,1]
	v_pk_fma_f32 v[4:5], v[54:55], v[106:107], v[4:5] op_sel_hi:[1,0,1]
	s_waitcnt lgkmcnt(9)
	v_pk_fma_f32 v[10:11], v[56:57], v[108:109], v[10:11] op_sel_hi:[1,0,1]
	v_pk_fma_f32 v[8:9], v[54:55], v[108:109], v[8:9] op_sel_hi:[1,0,1]
	s_waitcnt lgkmcnt(8)
	v_pk_fma_f32 v[14:15], v[56:57], v[110:111], v[14:15] op_sel_hi:[1,0,1]
	v_pk_fma_f32 v[12:13], v[54:55], v[110:111], v[12:13] op_sel_hi:[1,0,1]
	s_waitcnt vmcnt(1)
	s_waitcnt lgkmcnt(7)
	v_pk_fma_f32 v[2:3], v[60:61], v[112:113], v[2:3] op_sel_hi:[1,0,1]
	v_pk_fma_f32 v[0:1], v[58:59], v[112:113], v[0:1] op_sel_hi:[1,0,1]
	s_waitcnt lgkmcnt(6)
	v_pk_fma_f32 v[6:7], v[60:61], v[114:115], v[6:7] op_sel_hi:[1,0,1]
	v_pk_fma_f32 v[4:5], v[58:59], v[114:115], v[4:5] op_sel_hi:[1,0,1]
	s_waitcnt lgkmcnt(5)
	v_pk_fma_f32 v[10:11], v[60:61], v[116:117], v[10:11] op_sel_hi:[1,0,1]
	v_pk_fma_f32 v[8:9], v[58:59], v[116:117], v[8:9] op_sel_hi:[1,0,1]
	s_waitcnt lgkmcnt(4)
	v_pk_fma_f32 v[14:15], v[60:61], v[118:119], v[14:15] op_sel_hi:[1,0,1]
	v_pk_fma_f32 v[12:13], v[58:59], v[118:119], v[12:13] op_sel_hi:[1,0,1]
	s_waitcnt vmcnt(0)
	s_waitcnt lgkmcnt(3)
	v_pk_fma_f32 v[2:3], v[64:65], v[120:121], v[2:3] op_sel_hi:[1,0,1]
	v_pk_fma_f32 v[0:1], v[62:63], v[120:121], v[0:1] op_sel_hi:[1,0,1]
	s_waitcnt lgkmcnt(2)
	v_pk_fma_f32 v[6:7], v[64:65], v[122:123], v[6:7] op_sel_hi:[1,0,1]
	v_pk_fma_f32 v[4:5], v[62:63], v[122:123], v[4:5] op_sel_hi:[1,0,1]
	s_waitcnt lgkmcnt(1)
	v_pk_fma_f32 v[10:11], v[64:65], v[124:125], v[10:11] op_sel_hi:[1,0,1]
	v_pk_fma_f32 v[8:9], v[62:63], v[124:125], v[8:9] op_sel_hi:[1,0,1]
	s_waitcnt lgkmcnt(0)
	v_pk_fma_f32 v[14:15], v[64:65], v[126:127], v[14:15] op_sel_hi:[1,0,1]
	v_pk_fma_f32 v[12:13], v[62:63], v[126:127], v[12:13] op_sel_hi:[1,0,1]
	s_mov_b32 s46, 64
	s_mov_b64 s[48:49], 0
	s_and_b64 vcc, exec, s[22:23]
	s_cbranch_vccz .LBB0_369
	s_lshl_b32 s20, s43, 12
	s_add_i32 s20, s20, 0
	v_lshlrev_b32_e32 v16, 2, v160
	v_and_b32_e32 v168, 0x3fc, v16
	v_lshl_add_u32 v22, v28, 4, s20
	v_add_u32_e32 v18, 0, v168
	v_and_b32_e32 v16, 0x3fffff00, v160
	ds_write_b128 v22, v[0:3]
	ds_write_b128 v22, v[4:7] offset:1024
	ds_write_b128 v22, v[8:11] offset:2048
	ds_write_b128 v22, v[12:15] offset:3072
	v_lshl_add_u32 v20, v16, 2, v18
	s_waitcnt vmcnt(0) lgkmcnt(0)
	s_barrier
	ds_read2st64_b32 v[0:1], v20 offset1:16
	ds_read2st64_b32 v[4:5], v20 offset0:32 offset1:48
	ds_read2st64_b32 v[6:7], v20 offset0:64 offset1:80
	s_add_u32 s4, s28, s4
	s_addc_u32 s5, s29, s5
	s_waitcnt lgkmcnt(2)
	v_add_f32_e32 v0, 0, v0
	v_add_f32_e32 v8, v0, v1
	ds_read2st64_b32 v[0:1], v20 offset0:96 offset1:112
	s_waitcnt lgkmcnt(2)
	v_add_f32_e32 v4, v8, v4
	v_add_f32_e32 v4, v4, v5
	v_and_b32_e32 v19, 0x3fffff00, v30
	s_add_u32 s4, s4, s18
	s_waitcnt lgkmcnt(1)
	v_add_f32_e32 v4, v4, v6
	v_lshl_add_u32 v21, v19, 2, v18
	s_addc_u32 s5, s5, s19
	v_add_f32_e32 v4, v4, v7
	v_mul_hi_i32_i24_e32 v17, 0x3800, v31
	v_mul_i32_i24_e32 v16, 0x3800, v31
	v_lshl_add_u64 v[2:3], s[4:5], 0, v[168:169]
	s_waitcnt lgkmcnt(0)
	v_add_f32_e32 v0, v4, v0
	ds_read2st64_b32 v[4:5], v21 offset1:16
	v_add_f32_e32 v6, v0, v1
	v_lshl_add_u64 v[0:1], v[2:3], 0, v[16:17]
	global_store_dword v[0:1], v6, off
	ds_read2st64_b32 v[0:1], v21 offset0:32 offset1:48
	ds_read2st64_b32 v[6:7], v21 offset0:64 offset1:80
	s_waitcnt lgkmcnt(2)
	v_add_f32_e32 v4, 0, v4
	v_add_f32_e32 v8, v4, v5
	ds_read2st64_b32 v[4:5], v21 offset0:96 offset1:112
	s_waitcnt lgkmcnt(2)
	v_add_f32_e32 v0, v8, v0
	v_add_f32_e32 v0, v0, v1
	s_waitcnt lgkmcnt(1)
	v_add_f32_e32 v0, v0, v6
	v_add_f32_e32 v0, v0, v7
	v_mul_hi_i32_i24_e32 v19, 0x3800, v29
	v_mul_i32_i24_e32 v18, 0x3800, v29
	s_waitcnt lgkmcnt(0)
	v_add_f32_e32 v0, v0, v4
	v_add_f32_e32 v4, v0, v5
	v_lshl_add_u64 v[0:1], v[2:3], 0, v[18:19]
	global_store_dword v[0:1], v4, off
	s_waitcnt vmcnt(0) lgkmcnt(0)
	s_barrier

.Lgemv2b_loop:
	v_add_u32_e32 v37, s12, v32
	s_waitcnt vmcnt(8)
	ds_bpermute_b32 v66, v37, v33
	ds_bpermute_b32 v68, v37, v34
	ds_bpermute_b32 v70, v37, v35
	ds_bpermute_b32 v72, v37, v36
	ds_bpermute_b32 v74, v37, v33 offset:4
	ds_bpermute_b32 v76, v37, v34 offset:4
	ds_bpermute_b32 v78, v37, v35 offset:4
	ds_bpermute_b32 v80, v37, v36 offset:4
	ds_bpermute_b32 v82, v37, v33 offset:8
	ds_bpermute_b32 v84, v37, v34 offset:8
	ds_bpermute_b32 v86, v37, v35 offset:8
	ds_bpermute_b32 v88, v37, v36 offset:8
	ds_bpermute_b32 v90, v37, v33 offset:12
	ds_bpermute_b32 v92, v37, v34 offset:12
	ds_bpermute_b32 v94, v37, v35 offset:12
	ds_bpermute_b32 v96, v37, v36 offset:12
	ds_bpermute_b32 v98, v37, v33 offset:16
	ds_bpermute_b32 v100, v37, v34 offset:16
	ds_bpermute_b32 v26, v37, v35 offset:16
	ds_bpermute_b32 v102, v37, v36 offset:16
	ds_bpermute_b32 v104, v37, v33 offset:20
	ds_bpermute_b32 v106, v37, v34 offset:20
	ds_bpermute_b32 v108, v37, v35 offset:20
	ds_bpermute_b32 v110, v37, v36 offset:20
	ds_bpermute_b32 v112, v37, v33 offset:24
	ds_bpermute_b32 v114, v37, v34 offset:24
	ds_bpermute_b32 v116, v37, v35 offset:24
	ds_bpermute_b32 v118, v37, v36 offset:24
	ds_bpermute_b32 v120, v37, v33 offset:28
	ds_bpermute_b32 v122, v37, v34 offset:28
	ds_bpermute_b32 v124, v37, v35 offset:28
	ds_bpermute_b32 v126, v37, v36 offset:28
	s_add_i32 s12, s12, 32
	s_cmpk_eq_i32 s12, 0xe0
	s_waitcnt vmcnt(7)
	s_waitcnt lgkmcnt(14)
	v_pk_fma_f32 v[2:3], v[18:19], v[66:67], v[2:3] op_sel_hi:[1,0,1]
	v_pk_fma_f32 v[0:1], v[16:17], v[66:67], v[0:1] op_sel_hi:[1,0,1]
	v_pk_fma_f32 v[6:7], v[18:19], v[68:69], v[6:7] op_sel_hi:[1,0,1]
	v_pk_fma_f32 v[4:5], v[16:17], v[68:69], v[4:5] op_sel_hi:[1,0,1]
	v_pk_fma_f32 v[10:11], v[18:19], v[70:71], v[10:11] op_sel_hi:[1,0,1]
	v_pk_fma_f32 v[8:9], v[16:17], v[70:71], v[8:9] op_sel_hi:[1,0,1]
	v_pk_fma_f32 v[14:15], v[18:19], v[72:73], v[14:15] op_sel_hi:[1,0,1]
	v_pk_fma_f32 v[12:13], v[16:17], v[72:73], v[12:13] op_sel_hi:[1,0,1]
	v_lshl_add_u64 v[140:141], v[140:141], 0, s[6:7]
	global_load_dwordx4 v[16:19], v[140:141], off
	s_waitcnt vmcnt(7)
	v_pk_fma_f32 v[2:3], v[40:41], v[74:75], v[2:3] op_sel_hi:[1,0,1]
	v_pk_fma_f32 v[0:1], v[38:39], v[74:75], v[0:1] op_sel_hi:[1,0,1]
	v_pk_fma_f32 v[6:7], v[40:41], v[76:77], v[6:7] op_sel_hi:[1,0,1]
	v_pk_fma_f32 v[4:5], v[38:39], v[76:77], v[4:5] op_sel_hi:[1,0,1]
	v_pk_fma_f32 v[10:11], v[40:41], v[78:79], v[10:11] op_sel_hi:[1,0,1]
	v_pk_fma_f32 v[8:9], v[38:39], v[78:79], v[8:9] op_sel_hi:[1,0,1]
	v_pk_fma_f32 v[14:15], v[40:41], v[80:81], v[14:15] op_sel_hi:[1,0,1]
	v_pk_fma_f32 v[12:13], v[38:39], v[80:81], v[12:13] op_sel_hi:[1,0,1]
	v_lshl_add_u64 v[142:143], v[142:143], 0, s[6:7]
	global_load_dwordx4 v[38:41], v[142:143], off
	s_waitcnt vmcnt(7)
	v_pk_fma_f32 v[2:3], v[44:45], v[82:83], v[2:3] op_sel_hi:[1,0,1]
	v_pk_fma_f32 v[0:1], v[42:43], v[82:83], v[0:1] op_sel_hi:[1,0,1]
	v_pk_fma_f32 v[6:7], v[44:45], v[84:85], v[6:7] op_sel_hi:[1,0,1]
	v_pk_fma_f32 v[4:5], v[42:43], v[84:85], v[4:5] op_sel_hi:[1,0,1]
	v_pk_fma_f32 v[10:11], v[44:45], v[86:87], v[10:11] op_sel_hi:[1,0,1]
	v_pk_fma_f32 v[8:9], v[42:43], v[86:87], v[8:9] op_sel_hi:[1,0,1]
	v_pk_fma_f32 v[14:15], v[44:45], v[88:89], v[14:15] op_sel_hi:[1,0,1]
	v_pk_fma_f32 v[12:13], v[42:43], v[88:89], v[12:13] op_sel_hi:[1,0,1]
	v_lshl_add_u64 v[144:145], v[144:145], 0, s[6:7]
	global_load_dwordx4 v[42:45], v[144:145], off
	s_waitcnt vmcnt(7)
	v_pk_fma_f32 v[2:3], v[48:49], v[90:91], v[2:3] op_sel_hi:[1,0,1]
	v_pk_fma_f32 v[0:1], v[46:47], v[90:91], v[0:1] op_sel_hi:[1,0,1]
	v_pk_fma_f32 v[6:7], v[48:49], v[92:93], v[6:7] op_sel_hi:[1,0,1]
	v_pk_fma_f32 v[4:5], v[46:47], v[92:93], v[4:5] op_sel_hi:[1,0,1]
	v_pk_fma_f32 v[10:11], v[48:49], v[94:95], v[10:11] op_sel_hi:[1,0,1]
	v_pk_fma_f32 v[8:9], v[46:47], v[94:95], v[8:9] op_sel_hi:[1,0,1]
	v_pk_fma_f32 v[14:15], v[48:49], v[96:97], v[14:15] op_sel_hi:[1,0,1]
	v_pk_fma_f32 v[12:13], v[46:47], v[96:97], v[12:13] op_sel_hi:[1,0,1]
	v_lshl_add_u64 v[146:147], v[146:147], 0, s[6:7]
	global_load_dwordx4 v[46:49], v[146:147], off
	s_waitcnt vmcnt(7)
	v_pk_fma_f32 v[2:3], v[52:53], v[98:99], v[2:3] op_sel_hi:[1,0,1]
	v_pk_fma_f32 v[0:1], v[50:51], v[98:99], v[0:1] op_sel_hi:[1,0,1]
	v_pk_fma_f32 v[6:7], v[52:53], v[100:101], v[6:7] op_sel_hi:[1,0,1]
	v_pk_fma_f32 v[4:5], v[50:51], v[100:101], v[4:5] op_sel_hi:[1,0,1]
	s_waitcnt lgkmcnt(13)
	v_pk_fma_f32 v[10:11], v[52:53], v[26:27], v[10:11] op_sel_hi:[1,0,1]
	v_pk_fma_f32 v[8:9], v[50:51], v[26:27], v[8:9] op_sel_hi:[1,0,1]
	s_waitcnt lgkmcnt(12)
	v_pk_fma_f32 v[14:15], v[52:53], v[102:103], v[14:15] op_sel_hi:[1,0,1]
	v_pk_fma_f32 v[12:13], v[50:51], v[102:103], v[12:13] op_sel_hi:[1,0,1]
	v_lshl_add_u64 v[148:149], v[148:149], 0, s[6:7]
	global_load_dwordx4 v[50:53], v[148:149], off
	s_waitcnt vmcnt(7)
	s_waitcnt lgkmcnt(11)
	v_pk_fma_f32 v[2:3], v[56:57], v[104:105], v[2:3] op_sel_hi:[1,0,1]
	v_pk_fma_f32 v[0:1], v[54:55], v[104:105], v[0:1] op_sel_hi:[1,0,1]
	s_waitcnt lgkmcnt(10)
	v_pk_fma_f32 v[6:7], v[56:57], v[106:107], v[6:7] op_sel_hi:[1,0,1]
	v_pk_fma_f32 v[4:5], v[54:55], v[106:107], v[4:5] op_sel_hi:[1,0,1]
	s_waitcnt lgkmcnt(9)
	v_pk_fma_f32 v[10:11], v[56:57], v[108:109], v[10:11] op_sel_hi:[1,0,1]
	v_pk_fma_f32 v[8:9], v[54:55], v[108:109], v[8:9] op_sel_hi:[1,0,1]
	s_waitcnt lgkmcnt(8)
	v_pk_fma_f32 v[14:15], v[56:57], v[110:111], v[14:15] op_sel_hi:[1,0,1]
	v_pk_fma_f32 v[12:13], v[54:55], v[110:111], v[12:13] op_sel_hi:[1,0,1]
	v_lshl_add_u64 v[150:151], v[150:151], 0, s[6:7]
	global_load_dwordx4 v[54:57], v[150:151], off
	s_waitcnt vmcnt(7)
	s_waitcnt lgkmcnt(7)
	v_pk_fma_f32 v[2:3], v[60:61], v[112:113], v[2:3] op_sel_hi:[1,0,1]
	v_pk_fma_f32 v[0:1], v[58:59], v[112:113], v[0:1] op_sel_hi:[1,0,1]
	s_waitcnt lgkmcnt(6)
	v_pk_fma_f32 v[6:7], v[60:61], v[114:115], v[6:7] op_sel_hi:[1,0,1]
	v_pk_fma_f32 v[4:5], v[58:59], v[114:115], v[4:5] op_sel_hi:[1,0,1]
	s_waitcnt lgkmcnt(5)
	v_pk_fma_f32 v[10:11], v[60:61], v[116:117], v[10:11] op_sel_hi:[1,0,1]
	v_pk_fma_f32 v[8:9], v[58:59], v[116:117], v[8:9] op_sel_hi:[1,0,1]
	s_waitcnt lgkmcnt(4)
	v_pk_fma_f32 v[14:15], v[60:61], v[118:119], v[14:15] op_sel_hi:[1,0,1]
	v_pk_fma_f32 v[12:13], v[58:59], v[118:119], v[12:13] op_sel_hi:[1,0,1]
	v_lshl_add_u64 v[152:153], v[152:153], 0, s[6:7]
	global_load_dwordx4 v[58:61], v[152:153], off
	s_waitcnt vmcnt(7)
	s_waitcnt lgkmcnt(3)
	v_pk_fma_f32 v[2:3], v[64:65], v[120:121], v[2:3] op_sel_hi:[1,0,1]
	v_pk_fma_f32 v[0:1], v[62:63], v[120:121], v[0:1] op_sel_hi:[1,0,1]
	s_waitcnt lgkmcnt(2)
	v_pk_fma_f32 v[6:7], v[64:65], v[122:123], v[6:7] op_sel_hi:[1,0,1]
	v_pk_fma_f32 v[4:5], v[62:63], v[122:123], v[4:5] op_sel_hi:[1,0,1]
	s_waitcnt lgkmcnt(1)
	v_pk_fma_f32 v[10:11], v[64:65], v[124:125], v[10:11] op_sel_hi:[1,0,1]
	v_pk_fma_f32 v[8:9], v[62:63], v[124:125], v[8:9] op_sel_hi:[1,0,1]
	s_waitcnt lgkmcnt(0)
	v_pk_fma_f32 v[14:15], v[64:65], v[126:127], v[14:15] op_sel_hi:[1,0,1]
	v_pk_fma_f32 v[12:13], v[62:63], v[126:127], v[12:13] op_sel_hi:[1,0,1]
	v_lshl_add_u64 v[154:155], v[154:155], 0, s[6:7]
	global_load_dwordx4 v[62:65], v[154:155], off
	s_cbranch_scc0 .Lgemv2b_loop
	v_add_u32_e32 v37, s12, v32
	s_waitcnt vmcnt(8)
	ds_bpermute_b32 v66, v37, v33
	ds_bpermute_b32 v68, v37, v34
	ds_bpermute_b32 v70, v37, v35
	ds_bpermute_b32 v72, v37, v36
	ds_bpermute_b32 v74, v37, v33 offset:4
	ds_bpermute_b32 v76, v37, v34 offset:4
	ds_bpermute_b32 v78, v37, v35 offset:4
	ds_bpermute_b32 v80, v37, v36 offset:4
	ds_bpermute_b32 v82, v37, v33 offset:8
	ds_bpermute_b32 v84, v37, v34 offset:8
	ds_bpermute_b32 v86, v37, v35 offset:8
	ds_bpermute_b32 v88, v37, v36 offset:8
	ds_bpermute_b32 v90, v37, v33 offset:12
	ds_bpermute_b32 v92, v37, v34 offset:12
	ds_bpermute_b32 v94, v37, v35 offset:12
	ds_bpermute_b32 v96, v37, v36 offset:12
	ds_bpermute_b32 v98, v37, v33 offset:16
	ds_bpermute_b32 v100, v37, v34 offset:16
	ds_bpermute_b32 v26, v37, v35 offset:16
	ds_bpermute_b32 v102, v37, v36 offset:16
	ds_bpermute_b32 v104, v37, v33 offset:20
	ds_bpermute_b32 v106, v37, v34 offset:20
	ds_bpermute_b32 v108, v37, v35 offset:20
	ds_bpermute_b32 v110, v37, v36 offset:20
	ds_bpermute_b32 v112, v37, v33 offset:24
	ds_bpermute_b32 v114, v37, v34 offset:24
	ds_bpermute_b32 v116, v37, v35 offset:24
	ds_bpermute_b32 v118, v37, v36 offset:24
	ds_bpermute_b32 v120, v37, v33 offset:28
	ds_bpermute_b32 v122, v37, v34 offset:28
	ds_bpermute_b32 v124, v37, v35 offset:28
	ds_bpermute_b32 v126, v37, v36 offset:28
	s_add_i32 s12, s12, 32
	s_waitcnt vmcnt(7)
	s_waitcnt lgkmcnt(14)
	v_pk_fma_f32 v[2:3], v[18:19], v[66:67], v[2:3] op_sel_hi:[1,0,1]
	v_pk_fma_f32 v[0:1], v[16:17], v[66:67], v[0:1] op_sel_hi:[1,0,1]
	v_pk_fma_f32 v[6:7], v[18:19], v[68:69], v[6:7] op_sel_hi:[1,0,1]
	v_pk_fma_f32 v[4:5], v[16:17], v[68:69], v[4:5] op_sel_hi:[1,0,1]
	v_pk_fma_f32 v[10:11], v[18:19], v[70:71], v[10:11] op_sel_hi:[1,0,1]
	v_pk_fma_f32 v[8:9], v[16:17], v[70:71], v[8:9] op_sel_hi:[1,0,1]
	v_pk_fma_f32 v[14:15], v[18:19], v[72:73], v[14:15] op_sel_hi:[1,0,1]
	v_pk_fma_f32 v[12:13], v[16:17], v[72:73], v[12:13] op_sel_hi:[1,0,1]
	s_waitcnt vmcnt(6)
	v_pk_fma_f32 v[2:3], v[40:41], v[74:75], v[2:3] op_sel_hi:[1,0,1]
	v_pk_fma_f32 v[0:1], v[38:39], v[74:75], v[0:1] op_sel_hi:[1,0,1]
	v_pk_fma_f32 v[6:7], v[40:41], v[76:77], v[6:7] op_sel_hi:[1,0,1]
	v_pk_fma_f32 v[4:5], v[38:39], v[76:77], v[4:5] op_sel_hi:[1,0,1]
	v_pk_fma_f32 v[10:11], v[40:41], v[78:79], v[10:11] op_sel_hi:[1,0,1]
	v_pk_fma_f32 v[8:9], v[38:39], v[78:79], v[8:9] op_sel_hi:[1,0,1]
	v_pk_fma_f32 v[14:15], v[40:41], v[80:81], v[14:15] op_sel_hi:[1,0,1]
	v_pk_fma_f32 v[12:13], v[38:39], v[80:81], v[12:13] op_sel_hi:[1,0,1]
	s_waitcnt vmcnt(5)
	v_pk_fma_f32 v[2:3], v[44:45], v[82:83], v[2:3] op_sel_hi:[1,0,1]
	v_pk_fma_f32 v[0:1], v[42:43], v[82:83], v[0:1] op_sel_hi:[1,0,1]
	v_pk_fma_f32 v[6:7], v[44:45], v[84:85], v[6:7] op_sel_hi:[1,0,1]
	v_pk_fma_f32 v[4:5], v[42:43], v[84:85], v[4:5] op_sel_hi:[1,0,1]
	v_pk_fma_f32 v[10:11], v[44:45], v[86:87], v[10:11] op_sel_hi:[1,0,1]
	v_pk_fma_f32 v[8:9], v[42:43], v[86:87], v[8:9] op_sel_hi:[1,0,1]
	v_pk_fma_f32 v[14:15], v[44:45], v[88:89], v[14:15] op_sel_hi:[1,0,1]
	v_pk_fma_f32 v[12:13], v[42:43], v[88:89], v[12:13] op_sel_hi:[1,0,1]
	s_waitcnt vmcnt(4)
	v_pk_fma_f32 v[2:3], v[48:49], v[90:91], v[2:3] op_sel_hi:[1,0,1]
	v_pk_fma_f32 v[0:1], v[46:47], v[90:91], v[0:1] op_sel_hi:[1,0,1]
	v_pk_fma_f32 v[6:7], v[48:49], v[92:93], v[6:7] op_sel_hi:[1,0,1]
	v_pk_fma_f32 v[4:5], v[46:47], v[92:93], v[4:5] op_sel_hi:[1,0,1]
	v_pk_fma_f32 v[10:11], v[48:49], v[94:95], v[10:11] op_sel_hi:[1,0,1]
	v_pk_fma_f32 v[8:9], v[46:47], v[94:95], v[8:9] op_sel_hi:[1,0,1]
	v_pk_fma_f32 v[14:15], v[48:49], v[96:97], v[14:15] op_sel_hi:[1,0,1]
	v_pk_fma_f32 v[12:13], v[46:47], v[96:97], v[12:13] op_sel_hi:[1,0,1]
	s_waitcnt vmcnt(3)
	v_pk_fma_f32 v[2:3], v[52:53], v[98:99], v[2:3] op_sel_hi:[1,0,1]
	v_pk_fma_f32 v[0:1], v[50:51], v[98:99], v[0:1] op_sel_hi:[1,0,1]
	v_pk_fma_f32 v[6:7], v[52:53], v[100:101], v[6:7] op_sel_hi:[1,0,1]
	v_pk_fma_f32 v[4:5], v[50:51], v[100:101], v[4:5] op_sel_hi:[1,0,1]
	s_waitcnt lgkmcnt(13)
	v_pk_fma_f32 v[10:11], v[52:53], v[26:27], v[10:11] op_sel_hi:[1,0,1]
	v_pk_fma_f32 v[8:9], v[50:51], v[26:27], v[8:9] op_sel_hi:[1,0,1]
	s_waitcnt lgkmcnt(12)
	v_pk_fma_f32 v[14:15], v[52:53], v[102:103], v[14:15] op_sel_hi:[1,0,1]
	v_pk_fma_f32 v[12:13], v[50:51], v[102:103], v[12:13] op_sel_hi:[1,0,1]
	s_waitcnt vmcnt(2)
	s_waitcnt lgkmcnt(11)
	v_pk_fma_f32 v[2:3], v[56:57], v[104:105], v[2:3] op_sel_hi:[1,0,1]
	v_pk_fma_f32 v[0:1], v[54:55], v[104:105], v[0:1] op_sel_hi:[1,0,1]
	s_waitcnt lgkmcnt(10)
	v_pk_fma_f32 v[6:7], v[56:57], v[106:107], v[6:7] op_sel_hi:[1,0,1]
	v_pk_fma_f32 v[4:5], v[54:55], v[106:107], v[4:5] op_sel_hi:[1,0,1]
	s_waitcnt lgkmcnt(9)
	v_pk_fma_f32 v[10:11], v[56:57], v[108:109], v[10:11] op_sel_hi:[1,0,1]
	v_pk_fma_f32 v[8:9], v[54:55], v[108:109], v[8:9] op_sel_hi:[1,0,1]
	s_waitcnt lgkmcnt(8)
	v_pk_fma_f32 v[14:15], v[56:57], v[110:111], v[14:15] op_sel_hi:[1,0,1]
	v_pk_fma_f32 v[12:13], v[54:55], v[110:111], v[12:13] op_sel_hi:[1,0,1]
	s_waitcnt vmcnt(1)
	s_waitcnt lgkmcnt(7)
	v_pk_fma_f32 v[2:3], v[60:61], v[112:113], v[2:3] op_sel_hi:[1,0,1]
	v_pk_fma_f32 v[0:1], v[58:59], v[112:113], v[0:1] op_sel_hi:[1,0,1]
	s_waitcnt lgkmcnt(6)
	v_pk_fma_f32 v[6:7], v[60:61], v[114:115], v[6:7] op_sel_hi:[1,0,1]
	v_pk_fma_f32 v[4:5], v[58:59], v[114:115], v[4:5] op_sel_hi:[1,0,1]
	s_waitcnt lgkmcnt(5)
	v_pk_fma_f32 v[10:11], v[60:61], v[116:117], v[10:11] op_sel_hi:[1,0,1]
	v_pk_fma_f32 v[8:9], v[58:59], v[116:117], v[8:9] op_sel_hi:[1,0,1]
	s_waitcnt lgkmcnt(4)
	v_pk_fma_f32 v[14:15], v[60:61], v[118:119], v[14:15] op_sel_hi:[1,0,1]
	v_pk_fma_f32 v[12:13], v[58:59], v[118:119], v[12:13] op_sel_hi:[1,0,1]
	s_waitcnt vmcnt(0)
	s_waitcnt lgkmcnt(3)
	v_pk_fma_f32 v[2:3], v[64:65], v[120:121], v[2:3] op_sel_hi:[1,0,1]
	v_pk_fma_f32 v[0:1], v[62:63], v[120:121], v[0:1] op_sel_hi:[1,0,1]
	s_waitcnt lgkmcnt(2)
	v_pk_fma_f32 v[6:7], v[64:65], v[122:123], v[6:7] op_sel_hi:[1,0,1]
	v_pk_fma_f32 v[4:5], v[62:63], v[122:123], v[4:5] op_sel_hi:[1,0,1]
	s_waitcnt lgkmcnt(1)
	v_pk_fma_f32 v[10:11], v[64:65], v[124:125], v[10:11] op_sel_hi:[1,0,1]
	v_pk_fma_f32 v[8:9], v[62:63], v[124:125], v[8:9] op_sel_hi:[1,0,1]
	s_waitcnt lgkmcnt(0)
	v_pk_fma_f32 v[14:15], v[64:65], v[126:127], v[14:15] op_sel_hi:[1,0,1]
	v_pk_fma_f32 v[12:13], v[62:63], v[126:127], v[12:13] op_sel_hi:[1,0,1]
	s_mov_b32 s15, 64
	s_mov_b64 s[12:13], 0
	s_and_b64 vcc, exec, s[10:11]
	s_cbranch_vccz .LBB0_391
	v_lshlrev_b32_e32 v20, 2, v160
	s_lshl_b32 s7, s43, 12
	v_and_b32_e32 v168, 0x3fc, v20
	s_add_i32 s7, s7, 0
	v_add_u32_e32 v20, 0, v168
	v_and_b32_e32 v21, 0x3fffff00, v160
	v_and_b32_e32 v22, 0x3fffff00, v29
	v_lshl_add_u32 v21, v21, 2, v20
	v_lshl_add_u32 v20, v22, 2, v20
	v_lshl_add_u32 v22, v28, 4, s7
	ds_write_b128 v22, v[0:3]
	ds_write_b128 v22, v[4:7] offset:1024
	ds_write_b128 v22, v[8:11] offset:2048
	ds_write_b128 v22, v[12:15] offset:3072
	s_waitcnt vmcnt(0) lgkmcnt(0)
	s_barrier
	ds_read2st64_b32 v[0:1], v21 offset1:16
	ds_read2st64_b32 v[4:5], v21 offset0:32 offset1:48
	s_mul_i32 s6, s31, 3
	ds_read2st64_b32 v[6:7], v21 offset0:64 offset1:80
	s_add_i32 s6, s30, s6
	s_waitcnt lgkmcnt(2)
	v_add_f32_e32 v0, 0, v0
	s_mul_hi_u32 s10, s6, 0xe000
	s_mul_i32 s6, s6, 0xe000
	v_add_f32_e32 v8, v0, v1
	ds_read2st64_b32 v[0:1], v21 offset0:96 offset1:112
	s_add_u32 s6, s28, s6
	s_waitcnt lgkmcnt(2)
	v_add_f32_e32 v4, v8, v4
	s_addc_u32 s10, s29, s10
	v_add_f32_e32 v4, v4, v5
	s_add_u32 s4, s6, s4
	s_waitcnt lgkmcnt(1)
	v_add_f32_e32 v4, v4, v6
	s_addc_u32 s5, s10, s5
	v_add_f32_e32 v4, v4, v7
	v_mul_hi_i32_i24_e32 v17, 0x3800, v31
	v_mul_i32_i24_e32 v16, 0x3800, v31
	v_lshl_add_u64 v[2:3], s[4:5], 0, v[168:169]
	s_waitcnt lgkmcnt(0)
	v_add_f32_e32 v0, v4, v0
	ds_read2st64_b32 v[4:5], v20 offset1:16
	v_add_f32_e32 v6, v0, v1
	v_lshl_add_u64 v[0:1], v[2:3], 0, v[16:17]
	global_store_dword v[0:1], v6, off
	ds_read2st64_b32 v[0:1], v20 offset0:32 offset1:48
	ds_read2st64_b32 v[6:7], v20 offset0:64 offset1:80
	s_waitcnt lgkmcnt(2)
	v_add_f32_e32 v4, 0, v4
	v_add_f32_e32 v8, v4, v5
	ds_read2st64_b32 v[4:5], v20 offset0:96 offset1:112
	s_waitcnt lgkmcnt(2)
	v_add_f32_e32 v0, v8, v0
	v_add_f32_e32 v0, v0, v1
	s_waitcnt lgkmcnt(1)
	v_add_f32_e32 v0, v0, v6
	v_add_f32_e32 v0, v0, v7
	v_mul_hi_i32_i24_e32 v19, 0x3800, v30
	v_mul_i32_i24_e32 v18, 0x3800, v30
	s_waitcnt lgkmcnt(0)
	v_add_f32_e32 v0, v0, v4
	v_add_f32_e32 v4, v0, v5
	v_lshl_add_u64 v[0:1], v[2:3], 0, v[18:19]
	global_store_dword v[0:1], v4, off
	s_waitcnt vmcnt(0) lgkmcnt(0)
	s_barrier
